# output-projection GEMMs walk each XCD's row groups in reverse (the rows the preceding phase wrote last are read first, while still in the Infinity Cache)
# speedup vs baseline: 1.0027x; 1.0027x over previous
;     __host__ __device__ bool next(int i, Unit& u) const {
;         const long L = (long)i * G + c; if (L >= nwg) return false;
;         int wgid = (int)L; { const int q = nwg / NXCD, r = nwg % NXCD, xcd = wgid % NXCD, off = wgid / NXCD; wgid = (xcd < r ? xcd * (q + 1) : r * (q + 1) + (xcd - r) * q) + off; }
;         const int nig = WGM * nN, gid = wgid / nig, fm = gid * WGM, gsz = (nM - fm) < WGM ? (nM - fm) : WGM;
;         u.pm = fm + ((wgid % nig) % gsz); u.pn = (wgid % nig) / gsz; return true;
.LBB0_1282:
	s_cmpk_lt_i32 s40, 0x400
	s_cselect_b64 s[8:9], -1, 0
	s_cmpk_gt_i32 s40, 0x3ff
	v_readfirstlane_b32 s18, v178
	s_cbranch_scc1 .LBB0_1288
	s_mov_b32 s24, s40
	s_cmpk_lg_u32 s80, 0x100
	s_cbranch_scc1 .Lres_norev0
	s_addk_i32 s24, 0x300
.Lres_norev0:
	s_ashr_i32 s2, s24, 31
	s_lshr_b32 s2, s2, 29
	s_add_i32 s10, s24, s2
	s_and_b32 s2, s10, -8
	s_sub_i32 s11, s24, s2
	s_cmp_gt_i32 s11, -1
	s_mov_b64 s[2:3], -1
	s_cbranch_scc0 .LBB0_1285
	s_lshl_b32 s12, s11, 7
	s_mov_b64 s[2:3], 0

;     __host__ __device__ bool next(int i, Unit& u) const {
;         const long L = (long)i * G + c; if (L >= nwg) return false;
;         int wgid = (int)L; { const int q = nwg / NXCD, r = nwg % NXCD, xcd = wgid % NXCD, off = wgid / NXCD; wgid = (xcd < r ? xcd * (q + 1) : r * (q + 1) + (xcd - r) * q) + off; }
;         const int nig = WGM * nN, gid = wgid / nig, fm = gid * WGM, gsz = (nM - fm) < WGM ? (nM - fm) : WGM;
;         u.pm = fm + ((wgid % nig) % gsz); u.pn = (wgid % nig) / gsz; return true;
; template <class Epi, class Sched, bool ALIGN_EPI = false, bool SP2 = false>
; __device__ __forceinline__ void gemm_phase(PG8_LAS unsigned char* lds, const Gemm g, const Sched& S, const Epi& E, const int tid) {
;     ...
;         const bool has_next = S.next(ui + 1, nxt);
;         const char* nA = has_next ? (const char*)g.A + (size_t)nxt.pm * tstep : cA; const char* nB = has_next ? (const char*)g.Bt + (size_t)nxt.pn * tstep : cB;
.LBB0_1294:
	s_add_i32 s59, s59, 1
	s_mul_i32 s0, s59, s63
	s_mul_hi_u32 s1, s59, s80
	s_add_i32 s1, s1, s0
	s_mul_i32 s0, s59, s80
	s_add_u32 s6, s0, s40
	s_addc_u32 s7, s1, s64
	v_cmp_gt_i64_e32 vcc, s[6:7], v[172:173]
	v_cmp_lt_i64_e64 s[0:1], s[6:7], v[170:171]
	s_cbranch_vccnz .LBB0_1300
	s_cmpk_lg_u32 s80, 0x100
	s_cbranch_scc1 .Lres_norev
	s_lshl_b32 s7, s59, 9
	s_sub_i32 s6, s6, s7
	s_addk_i32 s6, 0x300
.Lres_norev:
	s_ashr_i32 s7, s6, 31
	s_lshr_b32 s7, s7, 29
	s_add_i32 s20, s6, s7
	s_and_b32 s7, s20, -8
	s_sub_i32 s21, s6, s7
	s_cmp_gt_i32 s21, -1
	s_mov_b64 s[6:7], -1
	s_cbranch_scc0 .LBB0_1297
	s_lshl_b32 s65, s21, 7
	s_mov_b64 s[6:7], 0
